# stack8 + xb (A operand) touch-prefetch at P6 start
# baseline (speedup 1.0000x reference)
.LBB0_783:
	s_or_b64 exec, exec, s[0:1]
	s_waitcnt vmcnt(7) lgkmcnt(0)
	v_mov_b32_e32 v0, v210
	s_barrier
	v_lshl_add_u32 v236, s2, 9, v210
	v_mov_b32_e32 v237, 0
	v_lshlrev_b64 v[236:237], 7, v[236:237]
	s_add_u32 s98, s92, 0x4d00000
	s_addc_u32 s99, s93, 0
	v_lshl_add_u64 v[236:237], s[98:99], 0, v[236:237]
	global_load_dword v234, v[236:237], off
	s_mov_b64 s[100:101], 0x1000000
	v_lshl_add_u64 v[236:237], v[236:237], 0, s[100:101]
	global_load_dword v234, v[236:237], off
	v_lshl_add_u64 v[236:237], v[236:237], 0, s[100:101]
	global_load_dword v234, v[236:237], off
	v_lshl_add_u64 v[236:237], v[236:237], 0, s[100:101]
	global_load_dword v234, v[236:237], off
	v_lshl_add_u32 v236, s2, 9, v210
	v_mov_b32_e32 v237, 0
	v_lshlrev_b64 v[236:237], 7, v[236:237]
	s_add_u32 s98, s92, 0x1400000
	s_addc_u32 s99, s93, 0
	v_lshl_add_u64 v[236:237], s[98:99], 0, v[236:237]
	global_load_dword v234, v[236:237], off
	s_mov_b64 s[100:101], 0x1000000
	v_lshl_add_u64 v[236:237], v[236:237], 0, s[100:101]
	global_load_dword v234, v[236:237], off
	s_cmpk_lt_i32 s2, 0x60
	s_cselect_b64 s[0:1], -1, 0
	v_readfirstlane_b32 s4, v0
	s_cmp_lt_u32 s4, 64
	s_cselect_b64 s[4:5], -1, 0
	s_and_b64 s[0:1], s[4:5], s[0:1]
	s_and_b64 vcc, exec, s[0:1]
	s_cbranch_vccz .LBB0_786
	v_mbcnt_hi_u32_b32 v1, -1, v211
	s_waitcnt vmcnt(6)
	v_and_b32_e32 v7, 64, v1
	v_add_u32_e32 v2, -1, v1
	v_cmp_lt_i32_e32 vcc, v2, v7
	v_add_u32_e32 v3, -2, v1
	v_add_u32_e32 v4, -4, v1
	v_cndmask_b32_e32 v2, v2, v1, vcc
	v_cmp_lt_i32_e32 vcc, v3, v7
	v_add_u32_e32 v5, -8, v1
	v_add_u32_e32 v6, -16, v1
	v_cndmask_b32_e32 v3, v3, v1, vcc
	v_cmp_lt_i32_e32 vcc, v4, v7
	s_waitcnt vmcnt(5)
	v_subrev_u32_e32 v8, 32, v1
	s_lshl_b64 s[0:1], s[2:3], 13
	v_cndmask_b32_e32 v4, v4, v1, vcc
	v_cmp_lt_i32_e32 vcc, v5, v7
	v_and_b32_e32 v0, 63, v0
	s_add_u32 s0, s92, s0
	v_cndmask_b32_e32 v5, v5, v1, vcc
	v_cmp_lt_i32_e32 vcc, v6, v7
	v_cmp_gt_u32_e64 s[42:43], 32, v0
	v_cmp_gt_u32_e64 s[44:45], 16, v0
	v_cndmask_b32_e32 v6, v6, v1, vcc
	v_cmp_lt_i32_e32 vcc, v8, v7
	v_cmp_gt_u32_e64 s[46:47], 8, v0
	v_cmp_gt_u32_e64 s[48:49], 4, v0
	v_cndmask_b32_e32 v1, v8, v1, vcc
	v_cmp_gt_u32_e64 s[50:51], 2, v0
	v_cmp_eq_u32_e64 s[52:53], 0, v0
	v_lshlrev_b32_e32 v7, 2, v1
	v_lshlrev_b32_e32 v0, 7, v0
	v_mov_b32_e32 v1, 0
	s_addc_u32 s1, s93, s1
	v_lshl_add_u64 v[0:1], s[0:1], 0, v[0:1]
	s_mov_b64 s[0:1], 0x120000
	v_lshlrev_b32_e32 v2, 2, v2
	v_lshlrev_b32_e32 v3, 2, v3
	v_lshlrev_b32_e32 v4, 2, v4
	v_lshlrev_b32_e32 v5, 2, v5
	v_lshlrev_b32_e32 v6, 2, v6
	v_lshl_add_u64 v[0:1], v[0:1], 0, s[0:1]
	s_lshl_b64 s[0:1], s[94:95], 13
	s_mov_b32 s4, s2
	s_mov_b32 s5, 0xfff31000
